# XCD-hierarchical grid barrier (one L2 writeback per XCD) for seams 1-7; P3 first ticket static; G2 l0 epilogue pipelined; P0 silu loop batched
# speedup vs baseline: 1.0261x; 1.0146x over previous
; __device__ __forceinline__ void fast_grid_barrier(unsigned* base, int seam, int tid) {
;     asm volatile("s_waitcnt vmcnt(0)" ::: "memory");
;     __syncthreads();
;     if (tid == 0) {
;         unsigned* cnt = base + seam * 128;
;         unsigned* flg = cnt + 64;
;         __builtin_amdgcn_fence(__ATOMIC_RELEASE, "agent");
;         asm volatile("s_waitcnt vmcnt(0)" ::: "memory");
;         const unsigned old = __hip_atomic_fetch_add(cnt, 1u, __ATOMIC_RELAXED, __HIP_MEMORY_SCOPE_AGENT);
;         if (old == gridDim.x - 1) __hip_atomic_store(flg, 1u, __ATOMIC_RELAXED, __HIP_MEMORY_SCOPE_AGENT);
;         else { unsigned sp = 0; while (__hip_atomic_load(flg, __ATOMIC_RELAXED, __HIP_MEMORY_SCOPE_AGENT) == 0u) { __builtin_amdgcn_s_sleep(2); if (++sp > (1u << 22)) break; } }
;         __builtin_amdgcn_fence(__ATOMIC_ACQUIRE, "agent");
;         asm volatile("s_waitcnt vmcnt(0)" ::: "memory");
;     }
;     __syncthreads();
; }
; __global__ void __launch_bounds__(512, 2) hybrid_fwd(Args a) {
;     ...
;     const int tid = threadIdx.x, lane = tid & 63, wid = __builtin_amdgcn_readfirstlane(tid >> 6);
;     const int lo = a.ph_lo, hi = a.ph_hi;
;     ...
;     if (hi > NPHASE) cg::this_grid().sync();
_Z10hybrid_fwd4Args:
	s_load_dwordx4 s[44:47], s[0:1], 0x90
	v_and_b32_e32 v202, 0x3ff, v0
	s_mov_b64 s[84:85], s[0:1]
	s_movk_i32 s0, 0x3ff
	v_readfirstlane_b32 s86, v202
	s_waitcnt lgkmcnt(0)
	s_getreg_b32 s98, hwreg(HW_REG_XCC_ID, 0, 4)
	v_cmp_eq_u32_e32 vcc, 0, v202
	s_and_saveexec_b64 s[4:5], vcc
	s_cbranch_execz .Lcensus_done
	s_add_u32 s6, s44, 0x1400
	s_addc_u32 s7, s45, 0
	s_lshl_b32 s3, s98, 2
	v_mov_b32_e32 v1, s3
	v_mov_b32_e32 v2, 1
	global_atomic_add v1, v1, v2, s[6:7] sc0
	s_waitcnt vmcnt(0)
	v_cmp_eq_u32_e32 vcc, 0, v1
	s_and_b64 exec, exec, vcc
	s_cbranch_execz .Lcensus_done
	v_mov_b32_e32 v1, 0
	global_atomic_add v1, v2, s[6:7] offset:64
.Lcensus_done:
	s_or_b64 exec, exec, s[4:5]
	s_cmp_gt_i32 s47, 9
	s_cselect_b64 s[4:5], -1, 0
	v_writelane_b32 v249, s4, 0
	s_cmp_lt_i32 s47, 10
	s_nop 0
	v_writelane_b32 v249, s5, 1
	s_cbranch_scc1 .LBB0_12
	v_lshrrev_b32_e32 v1, 20, v0
	v_lshrrev_b32_e32 v0, 10, v0
	v_or_b32_e32 v0, v0, v1
	v_and_or_b32 v0, v0, s0, v202
	v_cmp_eq_u32_e32 vcc, 0, v0
	s_barrier
	s_and_saveexec_b64 s[0:1], vcc
	s_cbranch_execz .LBB0_11
	buffer_wbl2 sc1
	s_load_dwordx2 s[4:5], s[84:85], 0xf8
	s_mov_b64 s[6:7], exec
	v_mbcnt_lo_u32_b32 v0, s6, 0
	v_mbcnt_hi_u32_b32 v0, s7, v0
	v_cmp_eq_u32_e32 vcc, 0, v0
	s_waitcnt lgkmcnt(0)
	s_load_dword s3, s[4:5], 0x28
	s_and_saveexec_b64 s[8:9], vcc
	s_cbranch_execz .LBB0_4
	s_bcnt1_i32_b64 s6, s[6:7]
	v_mov_b32_e32 v1, 0
	v_mov_b32_e32 v2, s6
	global_atomic_add v1, v1, v2, s[4:5] offset:32 sc0

; __device__ __forceinline__ void fast_grid_barrier(unsigned* base, int seam, int tid) {
;     asm volatile("s_waitcnt vmcnt(0)" ::: "memory");
;     __syncthreads();
;     if (tid == 0) {
;         unsigned* cnt = base + seam * 128;
;         unsigned* flg = cnt + 64;
;         __builtin_amdgcn_fence(__ATOMIC_RELEASE, "agent");
;         asm volatile("s_waitcnt vmcnt(0)" ::: "memory");
;         const unsigned old = __hip_atomic_fetch_add(cnt, 1u, __ATOMIC_RELAXED, __HIP_MEMORY_SCOPE_AGENT);
;         if (old == gridDim.x - 1) __hip_atomic_store(flg, 1u, __ATOMIC_RELAXED, __HIP_MEMORY_SCOPE_AGENT);
;         else { unsigned sp = 0; while (__hip_atomic_load(flg, __ATOMIC_RELAXED, __HIP_MEMORY_SCOPE_AGENT) == 0u) { __builtin_amdgcn_s_sleep(2); if (++sp > (1u << 22)) break; } }
;         __builtin_amdgcn_fence(__ATOMIC_ACQUIRE, "agent");
;         asm volatile("s_waitcnt vmcnt(0)" ::: "memory");
;     }
;     __syncthreads();
; }
.LBB0_84:
	s_cmp_lt_i32 s47, 3
	s_cbranch_scc1 .LBB0_101
	s_waitcnt vmcnt(0)
	v_cmp_eq_u32_e32 vcc, 0, v202
	s_barrier
	s_and_saveexec_b64 s[0:1], vcc
	s_cbranch_execz .LBB0_100
	s_load_dwordx2 s[4:5], s[84:85], 0x90
	s_lshl_b32 s3, s98, 6
	v_mov_b32_e32 v0, s3
	v_mov_b32_e32 v2, 1
	s_waitcnt lgkmcnt(0)
	s_add_u32 s4, s4, 0x1400
	s_addc_u32 s5, s5, 0
	s_lshl_b32 s6, s98, 2
	v_mov_b32_e32 v1, s6
	v_mov_b32_e32 v2, 0
	global_load_dword v1, v1, s[4:5] sc1
	global_load_dword v2, v2, s[4:5] offset:64 sc1
	s_waitcnt vmcnt(0)
	v_readfirstlane_b32 s99, v1
	v_readfirstlane_b32 s100, v2
	v_mov_b32_e32 v2, 1
	s_nop 3
	global_atomic_add v1, v0, v2, s[4:5] offset:128 sc0
	s_mul_i32 s6, s99, 1
	s_add_i32 s6, s6, -1
	s_waitcnt vmcnt(0)
	v_cmp_ne_u32_e32 vcc, s6, v1
	s_cbranch_vccnz .Lsm1_follow
	buffer_wbl2 sc1
	s_waitcnt vmcnt(0)
	s_sub_u32 s6, s4, s3
	s_subb_u32 s7, s5, 0
	global_atomic_add v1, v0, v2, s[6:7] offset:2176 sc0
	s_mul_i32 s3, s100, 1
	s_add_i32 s3, s3, -1
	s_waitcnt vmcnt(0)
	v_cmp_ne_u32_e32 vcc, s3, v1
	v_mov_b32_e32 v1, 1
	s_cbranch_vccnz .Lsm1_wtop
	global_store_dword v0, v1, s[6:7] offset:2304 sc1
	s_branch .Lsm1_topdone
.Lsm1_wtop:
	s_mov_b32 s3, 0x8000
.Lsm1_wtop_loop:
	global_load_dword v1, v0, s[6:7] offset:2304 sc1
	s_waitcnt vmcnt(0)
	v_cmp_le_u32_e32 vcc, 1, v1
	s_cbranch_vccnz .Lsm1_topdone
	s_sleep 1
	s_add_i32 s3, s3, -1
	s_cmp_lg_u32 s3, 0
	s_cbranch_scc1 .Lsm1_wtop_loop
.Lsm1_topdone:
	s_waitcnt vmcnt(0)
	buffer_inv sc1
	v_mov_b32_e32 v1, 1
	global_store_dword v0, v1, s[4:5] offset:1152 sc1
	s_waitcnt vmcnt(0)
	s_branch .Lsm1_done

; __device__ __forceinline__ void fast_grid_barrier(unsigned* base, int seam, int tid) {
;     ...
;         asm volatile("s_waitcnt vmcnt(0)" ::: "memory");
;         const unsigned old = __hip_atomic_fetch_add(cnt, 1u, __ATOMIC_RELAXED, __HIP_MEMORY_SCOPE_AGENT);
;         if (old == gridDim.x - 1) __hip_atomic_store(flg, 1u, __ATOMIC_RELAXED, __HIP_MEMORY_SCOPE_AGENT);
;         else { unsigned sp = 0; while (__hip_atomic_load(flg, __ATOMIC_RELAXED, __HIP_MEMORY_SCOPE_AGENT) == 0u) { __builtin_amdgcn_s_sleep(2); if (++sp > (1u << 22)) break; } }
;         __builtin_amdgcn_fence(__ATOMIC_ACQUIRE, "agent");
;         asm volatile("s_waitcnt vmcnt(0)" ::: "memory");
.Lsm1_follow_loop:
	global_load_dword v1, v0, s[4:5] offset:1152 sc1
	s_waitcnt vmcnt(0)
	v_cmp_le_u32_e32 vcc, 1, v1
	s_cbranch_vccnz .Lsm1_fdone
	s_sleep 1
	s_add_i32 s3, s3, -1
	s_cmp_lg_u32 s3, 0
	s_cbranch_scc1 .Lsm1_follow_loop
.Lsm1_fdone:
	buffer_inv sc1
	s_waitcnt vmcnt(0)
.Lsm1_done:
.LBB0_100:
	s_or_b64 exec, exec, s[0:1]
	s_barrier

; __device__ __forceinline__ void fast_grid_barrier(unsigned* base, int seam, int tid) {
;     asm volatile("s_waitcnt vmcnt(0)" ::: "memory");
;     __syncthreads();
;     if (tid == 0) {
;         unsigned* cnt = base + seam * 128;
;         unsigned* flg = cnt + 64;
;         __builtin_amdgcn_fence(__ATOMIC_RELEASE, "agent");
;         asm volatile("s_waitcnt vmcnt(0)" ::: "memory");
;         const unsigned old = __hip_atomic_fetch_add(cnt, 1u, __ATOMIC_RELAXED, __HIP_MEMORY_SCOPE_AGENT);
;         if (old == gridDim.x - 1) __hip_atomic_store(flg, 1u, __ATOMIC_RELAXED, __HIP_MEMORY_SCOPE_AGENT);
;         else { unsigned sp = 0; while (__hip_atomic_load(flg, __ATOMIC_RELAXED, __HIP_MEMORY_SCOPE_AGENT) == 0u) { __builtin_amdgcn_s_sleep(2); if (++sp > (1u << 22)) break; } }
;         __builtin_amdgcn_fence(__ATOMIC_ACQUIRE, "agent");
;         asm volatile("s_waitcnt vmcnt(0)" ::: "memory");
;     }
;     __syncthreads();
; }
.LBB0_167:
	s_waitcnt vmcnt(0)
	v_cmp_eq_u32_e32 vcc, 0, v202
	s_waitcnt vmcnt(0) lgkmcnt(0)
	s_barrier
	s_and_saveexec_b64 s[0:1], vcc
	s_cbranch_execz .LBB0_182
	s_load_dwordx2 s[4:5], s[84:85], 0x90
	s_lshl_b32 s3, s98, 6
	v_mov_b32_e32 v0, s3
	v_mov_b32_e32 v2, 1
	s_waitcnt lgkmcnt(0)
	s_add_u32 s4, s4, 0x1400
	s_addc_u32 s5, s5, 0
	global_atomic_add v1, v0, v2, s[4:5] offset:128 sc0
	s_mul_i32 s6, s99, 2
	s_add_i32 s6, s6, -1
	s_waitcnt vmcnt(0)
	v_cmp_ne_u32_e32 vcc, s6, v1
	s_cbranch_vccnz .Lsm2_follow
	buffer_wbl2 sc1
	s_waitcnt vmcnt(0)
	s_sub_u32 s6, s4, s3
	s_subb_u32 s7, s5, 0
	global_atomic_add v1, v0, v2, s[6:7] offset:2176 sc0
	s_mul_i32 s3, s100, 2
	s_add_i32 s3, s3, -1
	s_waitcnt vmcnt(0)
	v_cmp_ne_u32_e32 vcc, s3, v1
	v_mov_b32_e32 v1, 2
	s_cbranch_vccnz .Lsm2_wtop
	global_store_dword v0, v1, s[6:7] offset:2304 sc1
	s_branch .Lsm2_topdone

; __device__ __forceinline__ void fast_grid_barrier(unsigned* base, int seam, int tid) {
;     ...
;         asm volatile("s_waitcnt vmcnt(0)" ::: "memory");
;         const unsigned old = __hip_atomic_fetch_add(cnt, 1u, __ATOMIC_RELAXED, __HIP_MEMORY_SCOPE_AGENT);
;         if (old == gridDim.x - 1) __hip_atomic_store(flg, 1u, __ATOMIC_RELAXED, __HIP_MEMORY_SCOPE_AGENT);
;         else { unsigned sp = 0; while (__hip_atomic_load(flg, __ATOMIC_RELAXED, __HIP_MEMORY_SCOPE_AGENT) == 0u) { __builtin_amdgcn_s_sleep(2); if (++sp > (1u << 22)) break; } }
;         __builtin_amdgcn_fence(__ATOMIC_ACQUIRE, "agent");
;         asm volatile("s_waitcnt vmcnt(0)" ::: "memory");
.Lsm2_wtop_loop:
	global_load_dword v1, v0, s[6:7] offset:2304 sc1
	s_waitcnt vmcnt(0)
	v_cmp_le_u32_e32 vcc, 2, v1
	s_cbranch_vccnz .Lsm2_topdone
	s_sleep 1
	s_add_i32 s3, s3, -1
	s_cmp_lg_u32 s3, 0
	s_cbranch_scc1 .Lsm2_wtop_loop
.Lsm2_topdone:
	s_waitcnt vmcnt(0)
	buffer_inv sc1
	v_mov_b32_e32 v1, 2
	global_store_dword v0, v1, s[4:5] offset:1152 sc1
	s_waitcnt vmcnt(0)
	s_branch .Lsm2_done

; __device__ __forceinline__ void fast_grid_barrier(unsigned* base, int seam, int tid) {
;     ...
;         else { unsigned sp = 0; while (__hip_atomic_load(flg, __ATOMIC_RELAXED, __HIP_MEMORY_SCOPE_AGENT) == 0u) { __builtin_amdgcn_s_sleep(2); if (++sp > (1u << 22)) break; } }
;         __builtin_amdgcn_fence(__ATOMIC_ACQUIRE, "agent");
;         asm volatile("s_waitcnt vmcnt(0)" ::: "memory");
.Lsm2_follow_loop:
	global_load_dword v1, v0, s[4:5] offset:1152 sc1
	s_waitcnt vmcnt(0)
	v_cmp_le_u32_e32 vcc, 2, v1
	s_cbranch_vccnz .Lsm2_fdone
	s_sleep 1
	s_add_i32 s3, s3, -1
	s_cmp_lg_u32 s3, 0
	s_cbranch_scc1 .Lsm2_follow_loop

; #define LAS __attribute__((address_space(3)))
; #define p3_fetch(a_, b_, c_) (ubase + p3_fetch_(a_, b_, c_, pre, pre2, nxt_))
;     volatile LAS int* s_unit = (volatile LAS int*)(lds + LDS_BYTES - 64);
;     ...
;     int pre = 0, pre2 = 0, nxt_ = 0; if (tid == 0) { pre = (int)atomicAdd(counter, 1u); pre2 = (int)atomicAdd(counter, 1u); }
;     int u = p3_fetch(s_unit, counter, tid);
; template <int PH>
; __device__ __forceinline__ void run_phase(LAS unsigned char* lds, int tid, int wid, int lane) {
;     ...
;         } else if constexpr (sub == 2) {
;             LayerP lp;
;             lp.gv = a.in[6] + l * 256; lp.gws = a.in[7] + (size_t)l * 4 * 128 * 128; lp.gbs = a.in[8] + l * 512; lp.convw = a.in[9] + l * 4 * 768; lp.convb = a.in[10] + l * 768;
;             lp.bi = a.in[11] + l * 4; lp.bfv = a.in[12] + l * 4; lp.hn = a.in[13] + l * 384; lp.gq = a.in[14] + l * 64; lp.gk = a.in[15] + l * 64; lp.halo = (const bf16*)(ws + WS_HALO);
;             p3_phase(lds, PJ, gate, H, lp, (unsigned*)(ws + WS_CTL) + 64 * l, tid, P3_WID, lane);
.LBB0_183:
	s_cmp_gt_i32 s46, 3
	s_cselect_b64 s[0:1], -1, 0
	s_cmp_lt_i32 s47, 4
	s_cselect_b64 s[4:5], -1, 0
	s_or_b64 s[0:1], s[0:1], s[4:5]
	s_and_b64 vcc, exec, s[0:1]
	s_cbranch_vccnz .LBB0_561
	s_mov_b64 s[0:1], s[84:85]
	s_load_dwordx16 s[4:19], s[0:1], 0x30
	v_mov_b32_e32 v0, 0
	v_mov_b32_e32 v135, 0
	s_load_dwordx2 s[74:75], s[0:1], 0x90
	s_waitcnt lgkmcnt(0)
	v_writelane_b32 v249, s4, 8
	s_nop 1
	v_writelane_b32 v249, s5, 9
	v_writelane_b32 v249, s6, 10
	v_writelane_b32 v249, s7, 11
	v_writelane_b32 v249, s8, 12
	v_writelane_b32 v249, s9, 13
	v_writelane_b32 v249, s10, 14
	v_writelane_b32 v249, s11, 15
	v_writelane_b32 v249, s12, 16
	v_writelane_b32 v249, s13, 17
	v_writelane_b32 v249, s14, 18
	v_writelane_b32 v249, s15, 19
	v_writelane_b32 v249, s16, 20
	v_writelane_b32 v249, s17, 21
	v_writelane_b32 v249, s18, 22
	v_writelane_b32 v249, s19, 23
	s_load_dwordx4 s[4:7], s[0:1], 0x70
	s_waitcnt lgkmcnt(0)
	v_writelane_b32 v249, s4, 24
	s_nop 1
	v_writelane_b32 v249, s5, 25
	v_writelane_b32 v249, s6, 26
	v_writelane_b32 v249, s7, 27
	v_cmp_eq_u32_e64 s[4:5], 0, v202
	s_mov_b64 s[0:1], exec
	s_nop 0
	v_writelane_b32 v249, s4, 28
	s_nop 1
	v_writelane_b32 v249, s5, 29
	s_and_b64 s[4:5], s[0:1], s[4:5]
	s_mov_b64 exec, s[4:5]
	s_cbranch_execz .LBB0_190
	s_mov_b64 s[6:7], exec
	v_mbcnt_lo_u32_b32 v0, s6, 0
	v_mbcnt_hi_u32_b32 v0, s7, v0
	v_cmp_eq_u32_e32 vcc, 0, v0
	s_and_saveexec_b64 s[4:5], vcc
	s_cbranch_execz .LBB0_187
	s_bcnt1_i32_b64 s3, s[6:7]
	v_mov_b32_e32 v1, 0
	v_mov_b32_e32 v2, s3
	s_nop 0

; #define p3_fetch(a_, b_, c_) (ubase + p3_fetch_(a_, b_, c_, pre, pre2, nxt_))
;     ...
;     int pre = 0, pre2 = 0, nxt_ = 0; if (tid == 0) { pre = (int)atomicAdd(counter, 1u); pre2 = (int)atomicAdd(counter, 1u); }
;     int u = p3_fetch(s_unit, counter, tid);
.LBB0_189:
	s_or_b64 exec, exec, s[6:7]
	v_add_u32_e32 v135, s3, v0
	v_mov_b32_e32 v135, s2
	s_waitcnt vmcnt(0)
	v_readfirstlane_b32 s3, v2
	s_nop 1
	v_add_u32_e32 v0, s3, v1
	v_add_u32_e32 v0, 0x100, v0

; #define LAS __attribute__((address_space(3)))
; #define LBAR() do { asm volatile("s_waitcnt lgkmcnt(0)" ::: "memory"); __builtin_amdgcn_s_barrier(); asm volatile("" ::: "memory"); } while (0)
; __device__ __forceinline__ int p3_fetch_(volatile LAS int* s_unit, unsigned* counter, int tid, int& pre, int& pre2, int& nxt) {
;     LBAR();
;     if (tid == 0) { s_unit[0] = pre; s_unit[1] = pre2; }
;     LBAR();
;     const int u = __builtin_amdgcn_readfirstlane(s_unit[0]);
;     nxt = __builtin_amdgcn_readfirstlane(s_unit[1]);
;     if (tid == 0) { pre = pre2; pre2 = (int)atomicAdd(counter, 1u); }
;     return u;
.LBB0_195:
	s_or_b64 exec, exec, s[4:5]
	s_waitcnt vmcnt(0)
	v_readfirstlane_b32 s3, v2
	v_mov_b32_e32 v135, v0
	s_nop 0
	v_add_u32_e32 v139, s3, v1
	v_add_u32_e32 v139, 0x100, v139

; #define LAS __attribute__((address_space(3)))
; #define LBAR() do { asm volatile("s_waitcnt lgkmcnt(0)" ::: "memory"); __builtin_amdgcn_s_barrier(); asm volatile("" ::: "memory"); } while (0)
; #define p3_fetch(a_, b_, c_) (ubase + p3_fetch_(a_, b_, c_, pre, pre2, nxt_))
; __device__ __forceinline__ int p3_fetch_(volatile LAS int* s_unit, unsigned* counter, int tid, int& pre, int& pre2, int& nxt) {
;     LBAR();
;     if (tid == 0) { s_unit[0] = pre; s_unit[1] = pre2; }
;     LBAR();
;     const int u = __builtin_amdgcn_readfirstlane(s_unit[0]);
;     nxt = __builtin_amdgcn_readfirstlane(s_unit[1]);
;     if (tid == 0) { pre = pre2; pre2 = (int)atomicAdd(counter, 1u); }
;     return u;
;     ...
;     while (u < N_ML && u < uend) { mlstm_unit(lds, P, lp.halo, gate, Y, lp.convw, lp.convb, lp.bi, lp.bfv, lp.hn, u >> 2, u & 3, tid, wid, lane, mode); u = p3_fetch(s_unit, counter, tid); }
.LBB0_314:
	s_or_b64 exec, exec, s[4:5]
	s_waitcnt vmcnt(0)
	v_readfirstlane_b32 s4, v2
	v_mov_b32_e32 v135, v139
	s_nop 0
	v_add_u32_e32 v91, s4, v0
	v_add_u32_e32 v91, 0x100, v91

; #define LAS __attribute__((address_space(3)))
; #define LBAR() do { asm volatile("s_waitcnt lgkmcnt(0)" ::: "memory"); __builtin_amdgcn_s_barrier(); asm volatile("" ::: "memory"); } while (0)
; #define p3_fetch(a_, b_, c_) (ubase + p3_fetch_(a_, b_, c_, pre, pre2, nxt_))
; __device__ __forceinline__ int p3_fetch_(volatile LAS int* s_unit, unsigned* counter, int tid, int& pre, int& pre2, int& nxt) {
;     LBAR();
;     if (tid == 0) { s_unit[0] = pre; s_unit[1] = pre2; }
;     LBAR();
;     const int u = __builtin_amdgcn_readfirstlane(s_unit[0]);
;     nxt = __builtin_amdgcn_readfirstlane(s_unit[1]);
;     if (tid == 0) { pre = pre2; pre2 = (int)atomicAdd(counter, 1u); }
;     return u;
;     ...
;         while (u < N_ML + N_AT && u < uend) {
;             const int idx = u - N_ML, qb = 15 - idx / 192, rem = idx % 192;
;             const int nu = ubase + nxt_; const bool nvalid = nu < N_ML + N_AT && nu < uend; const int nidx = nu - N_ML, nqb = 15 - nidx / 192, nrem = nidx % 192;
;             attn_unit(lds, P, Y, lp.gq, lp.gk, rem / 6, rem % 6, qb, tid, wid, lane, have, pf, nvalid, nrem / 6, nrem % 6, nqb);
;             have = nvalid;
;             u = p3_fetch(s_unit, counter, tid);
.LBB0_482:
	s_or_b64 exec, exec, s[12:13]
	s_waitcnt vmcnt(0)
	v_readfirstlane_b32 s12, v25
	v_mov_b32_e32 v135, v91
	s_nop 0
	v_add_u32_e32 v41, s12, v24
	v_add_u32_e32 v41, 0x100, v41

; #define LAS __attribute__((address_space(3)))
; #define LBAR() do { asm volatile("s_waitcnt lgkmcnt(0)" ::: "memory"); __builtin_amdgcn_s_barrier(); asm volatile("" ::: "memory"); } while (0)
; #define p3_fetch(a_, b_, c_) (ubase + p3_fetch_(a_, b_, c_, pre, pre2, nxt_))
; __device__ __forceinline__ int p3_fetch_(volatile LAS int* s_unit, unsigned* counter, int tid, int& pre, int& pre2, int& nxt) {
;     LBAR();
;     if (tid == 0) { s_unit[0] = pre; s_unit[1] = pre2; }
;     LBAR();
;     const int u = __builtin_amdgcn_readfirstlane(s_unit[0]);
;     nxt = __builtin_amdgcn_readfirstlane(s_unit[1]);
;     if (tid == 0) { pre = pre2; pre2 = (int)atomicAdd(counter, 1u); }
;     return u;
;     ...
;     while (u < uend) { const int idx = u - N_ML - N_AT; gmlp_unit(lds, P, Y, lp.gws, lp.gbs, lp.gv, idx >> 4, (idx >> 2) & 3, idx & 3, tid, wid, lane); u = p3_fetch(s_unit, counter, tid); }
.LBB0_527:
	s_or_b64 exec, exec, s[18:19]
	s_waitcnt vmcnt(0) lgkmcnt(0)
	v_readfirstlane_b32 s0, v1
	v_mov_b32_e32 v135, v41
	s_nop 0
	v_add_u32_e32 v0, s0, v0
	v_add_u32_e32 v0, 0x100, v0

; __device__ __forceinline__ void fast_grid_barrier(unsigned* base, int seam, int tid) {
;     asm volatile("s_waitcnt vmcnt(0)" ::: "memory");
;     __syncthreads();
;     if (tid == 0) {
;         unsigned* cnt = base + seam * 128;
;         unsigned* flg = cnt + 64;
;         __builtin_amdgcn_fence(__ATOMIC_RELEASE, "agent");
;         asm volatile("s_waitcnt vmcnt(0)" ::: "memory");
;         const unsigned old = __hip_atomic_fetch_add(cnt, 1u, __ATOMIC_RELAXED, __HIP_MEMORY_SCOPE_AGENT);
;         if (old == gridDim.x - 1) __hip_atomic_store(flg, 1u, __ATOMIC_RELAXED, __HIP_MEMORY_SCOPE_AGENT);
;         else { unsigned sp = 0; while (__hip_atomic_load(flg, __ATOMIC_RELAXED, __HIP_MEMORY_SCOPE_AGENT) == 0u) { __builtin_amdgcn_s_sleep(2); if (++sp > (1u << 22)) break; } }
;         __builtin_amdgcn_fence(__ATOMIC_ACQUIRE, "agent");
;         asm volatile("s_waitcnt vmcnt(0)" ::: "memory");
;     }
;     __syncthreads();
; }
.LBB0_544:
	s_waitcnt lgkmcnt(0)
	s_cmp_lt_i32 s47, 5
	s_cbranch_scc1 .LBB0_561
	s_waitcnt vmcnt(0)
	s_waitcnt vmcnt(0)
	s_barrier
	s_mov_b64 s[0:1], exec
	v_readlane_b32 s4, v249, 28
	v_readlane_b32 s5, v249, 29
	s_and_b64 s[4:5], s[0:1], s[4:5]
	s_mov_b64 exec, s[4:5]
	s_cbranch_execz .LBB0_560
	s_load_dwordx2 s[4:5], s[84:85], 0x90
	s_lshl_b32 s3, s98, 6
	v_mov_b32_e32 v0, s3
	v_mov_b32_e32 v2, 1
	s_waitcnt lgkmcnt(0)
	s_add_u32 s4, s4, 0x1400
	s_addc_u32 s5, s5, 0
	global_atomic_add v1, v0, v2, s[4:5] offset:128 sc0
	s_mul_i32 s6, s99, 3
	s_add_i32 s6, s6, -1
	s_waitcnt vmcnt(0)
	v_cmp_ne_u32_e32 vcc, s6, v1
	s_cbranch_vccnz .Lsm3_follow
	buffer_wbl2 sc1
	s_waitcnt vmcnt(0)
	s_sub_u32 s6, s4, s3
	s_subb_u32 s7, s5, 0
	global_atomic_add v1, v0, v2, s[6:7] offset:2176 sc0
	s_mul_i32 s3, s100, 3
	s_add_i32 s3, s3, -1
	s_waitcnt vmcnt(0)
	v_cmp_ne_u32_e32 vcc, s3, v1
	v_mov_b32_e32 v1, 3
	s_cbranch_vccnz .Lsm3_wtop
	global_store_dword v0, v1, s[6:7] offset:2304 sc1
	s_branch .Lsm3_topdone

; __device__ __forceinline__ void fast_grid_barrier(unsigned* base, int seam, int tid) {
;     ...
;         asm volatile("s_waitcnt vmcnt(0)" ::: "memory");
;         const unsigned old = __hip_atomic_fetch_add(cnt, 1u, __ATOMIC_RELAXED, __HIP_MEMORY_SCOPE_AGENT);
;         if (old == gridDim.x - 1) __hip_atomic_store(flg, 1u, __ATOMIC_RELAXED, __HIP_MEMORY_SCOPE_AGENT);
;         else { unsigned sp = 0; while (__hip_atomic_load(flg, __ATOMIC_RELAXED, __HIP_MEMORY_SCOPE_AGENT) == 0u) { __builtin_amdgcn_s_sleep(2); if (++sp > (1u << 22)) break; } }
;         __builtin_amdgcn_fence(__ATOMIC_ACQUIRE, "agent");
;         asm volatile("s_waitcnt vmcnt(0)" ::: "memory");
.Lsm3_wtop_loop:
	global_load_dword v1, v0, s[6:7] offset:2304 sc1
	s_waitcnt vmcnt(0)
	v_cmp_le_u32_e32 vcc, 3, v1
	s_cbranch_vccnz .Lsm3_topdone
	s_sleep 1
	s_add_i32 s3, s3, -1
	s_cmp_lg_u32 s3, 0
	s_cbranch_scc1 .Lsm3_wtop_loop
.Lsm3_topdone:
	s_waitcnt vmcnt(0)
	buffer_inv sc1
	v_mov_b32_e32 v1, 3
	global_store_dword v0, v1, s[4:5] offset:1152 sc1
	s_waitcnt vmcnt(0)
	s_branch .Lsm3_done

; __device__ __forceinline__ void fast_grid_barrier(unsigned* base, int seam, int tid) {
;     ...
;         else { unsigned sp = 0; while (__hip_atomic_load(flg, __ATOMIC_RELAXED, __HIP_MEMORY_SCOPE_AGENT) == 0u) { __builtin_amdgcn_s_sleep(2); if (++sp > (1u << 22)) break; } }
;         __builtin_amdgcn_fence(__ATOMIC_ACQUIRE, "agent");
;         asm volatile("s_waitcnt vmcnt(0)" ::: "memory");
.Lsm3_follow_loop:
	global_load_dword v1, v0, s[4:5] offset:1152 sc1
	s_waitcnt vmcnt(0)
	v_cmp_le_u32_e32 vcc, 3, v1
	s_cbranch_vccnz .Lsm3_fdone
	s_sleep 1
	s_add_i32 s3, s3, -1
	s_cmp_lg_u32 s3, 0
	s_cbranch_scc1 .Lsm3_follow_loop

;     __device__ __forceinline__ void operator()(const f32x4 (&acc)[2][2][4][2], const pg8::Unit& u, int wr, int wc, int fr, int fq) const {
;         const int row0 = u.pm * 256 + wr * 64 + fr, col0 = u.pn * 256 + wc * 32 + 4 * fq;
;         const float* gp = gatev + (size_t)(u.pm >> 3) * 3072 + col0;
;         f32x4 gv[2][2];
; #pragma unroll
;         for (int bj = 0; bj < 2; ++bj)
; #pragma unroll
;             for (int n = 0; n < 2; ++n) gv[bj][n] = *(const f32x4*)(gp + bj * 128 + n * 16);
; #pragma unroll
;         for (int ai = 0; ai < 2; ++ai)
; #pragma unroll
;             for (int m = 0; m < 4; ++m) {
;                 const size_t off = (size_t)(row0 + ai * 128 + m * 16) * DM + col0;
; #pragma unroll
;                 for (int bj = 0; bj < 2; ++bj)
; #pragma unroll
;                     for (int n = 0; n < 2; ++n) {
;                         const f32x4 xv = *(const f32x4*)(xin + off + bj * 128 + n * 16);
;                         *(f32x4*)(out + off + bj * 128 + n * 16) = xv + gv[bj][n] * acc[ai][bj][m][n];
;                     }
;                 if (m == 3) asm volatile("" ::: "memory");
;             }
.LBB0_582:
	v_lshl_add_u32 v170, s30, 8, v158
	v_lshl_or_b32 v168, s56, 8, v160
	s_ashr_i32 s23, s30, 3
	v_ashrrev_i32_e32 v171, 31, v170
	s_mul_hi_i32 s25, s23, 0x3000
	s_mulk_i32 s23, 0x3000
	v_ashrrev_i32_e32 v169, 31, v168
	v_lshlrev_b64 v[130:131], 10, v[170:171]
	s_add_u32 s34, s49, s23
	v_lshl_add_u64 v[130:131], v[130:131], 0, v[168:169]
	s_addc_u32 s35, s50, s25
	v_lshlrev_b64 v[156:157], 2, v[130:131]
	v_lshl_add_u64 v[128:129], v[168:169], 2, s[34:35]
	global_load_dwordx4 v[140:143], v[128:129], off
	global_load_dwordx4 v[136:139], v[128:129], off offset:64
	global_load_dwordx4 v[132:135], v[128:129], off offset:512
	s_nop 0
	global_load_dwordx4 v[128:131], v[128:129], off offset:576
	s_andn2_b64 vcc, exec, s[4:5]
	s_mov_b64 s[4:5], -1
	s_mov_b64 s[36:37], s[0:1]
	global_load_dwordx4 v[164:167], v156, s[36:37]
	global_load_dwordx4 v[168:171], v156, s[36:37] offset:64
	global_load_dwordx4 v[172:175], v156, s[36:37] offset:512
	global_load_dwordx4 v[176:179], v156, s[36:37] offset:576
	s_add_u32 s36, s0, 0x10000
	s_addc_u32 s37, s1, 0
	global_load_dwordx4 v[180:183], v156, s[36:37]
	global_load_dwordx4 v[184:187], v156, s[36:37] offset:64
	global_load_dwordx4 v[188:191], v156, s[36:37] offset:512
	global_load_dwordx4 v[192:195], v156, s[36:37] offset:576
	s_add_u32 s36, s0, 0x20000
	s_addc_u32 s37, s1, 0
	global_load_dwordx4 v[196:199], v156, s[36:37]
	global_load_dwordx4 v[204:207], v156, s[36:37] offset:64
	global_load_dwordx4 v[208:211], v156, s[36:37] offset:512
	global_load_dwordx4 v[212:215], v156, s[36:37] offset:576
	s_waitcnt vmcnt(8)
	v_pk_fma_f32 v[166:167], v[126:127], v[142:143], v[166:167]
	v_pk_fma_f32 v[164:165], v[124:125], v[140:141], v[164:165]
	v_pk_fma_f32 v[170:171], v[122:123], v[138:139], v[170:171]
	v_pk_fma_f32 v[168:169], v[120:121], v[136:137], v[168:169]
	v_pk_fma_f32 v[174:175], v[118:119], v[134:135], v[174:175]
	v_pk_fma_f32 v[172:173], v[116:117], v[132:133], v[172:173]
	v_pk_fma_f32 v[178:179], v[106:107], v[130:131], v[178:179]
	v_pk_fma_f32 v[176:177], v[104:105], v[128:129], v[176:177]
	s_mov_b64 s[38:39], s[8:9]
	global_store_dwordx4 v156, v[164:167], s[38:39]
	global_store_dwordx4 v156, v[168:171], s[38:39] offset:64
	global_store_dwordx4 v156, v[172:175], s[38:39] offset:512
	global_store_dwordx4 v156, v[176:179], s[38:39] offset:576
	s_add_u32 s36, s0, 0x30000
	s_addc_u32 s37, s1, 0
	global_load_dwordx4 v[164:167], v156, s[36:37]
	global_load_dwordx4 v[168:171], v156, s[36:37] offset:64
	global_load_dwordx4 v[172:175], v156, s[36:37] offset:512
	global_load_dwordx4 v[176:179], v156, s[36:37] offset:576
	s_waitcnt vmcnt(12)
	v_pk_fma_f32 v[182:183], v[114:115], v[142:143], v[182:183]
	v_pk_fma_f32 v[180:181], v[112:113], v[140:141], v[180:181]
	v_pk_fma_f32 v[186:187], v[110:111], v[138:139], v[186:187]
	v_pk_fma_f32 v[184:185], v[108:109], v[136:137], v[184:185]
	v_pk_fma_f32 v[190:191], v[102:103], v[134:135], v[190:191]
	v_pk_fma_f32 v[188:189], v[100:101], v[132:133], v[188:189]
	v_pk_fma_f32 v[194:195], v[90:91], v[130:131], v[194:195]
	v_pk_fma_f32 v[192:193], v[88:89], v[128:129], v[192:193]
	s_add_u32 s38, s8, 0x10000
	s_addc_u32 s39, s9, 0
	global_store_dwordx4 v156, v[180:183], s[38:39]
	global_store_dwordx4 v156, v[184:187], s[38:39] offset:64
	global_store_dwordx4 v156, v[188:191], s[38:39] offset:512
	global_store_dwordx4 v156, v[192:195], s[38:39] offset:576
	s_add_u32 s36, s0, 0x80000
	s_addc_u32 s37, s1, 0
	global_load_dwordx4 v[180:183], v156, s[36:37]
	global_load_dwordx4 v[184:187], v156, s[36:37] offset:64
	global_load_dwordx4 v[188:191], v156, s[36:37] offset:512
	global_load_dwordx4 v[192:195], v156, s[36:37] offset:576
	s_waitcnt vmcnt(16)
	v_pk_fma_f32 v[198:199], v[98:99], v[142:143], v[198:199]
	v_pk_fma_f32 v[196:197], v[96:97], v[140:141], v[196:197]
	v_pk_fma_f32 v[206:207], v[94:95], v[138:139], v[206:207]
	v_pk_fma_f32 v[204:205], v[92:93], v[136:137], v[204:205]
	v_pk_fma_f32 v[210:211], v[86:87], v[134:135], v[210:211]
	v_pk_fma_f32 v[208:209], v[84:85], v[132:133], v[208:209]
	v_pk_fma_f32 v[214:215], v[74:75], v[130:131], v[214:215]
	v_pk_fma_f32 v[212:213], v[72:73], v[128:129], v[212:213]
	s_add_u32 s38, s8, 0x20000
	s_addc_u32 s39, s9, 0
	global_store_dwordx4 v156, v[196:199], s[38:39]
	global_store_dwordx4 v156, v[204:207], s[38:39] offset:64
	global_store_dwordx4 v156, v[208:211], s[38:39] offset:512
	global_store_dwordx4 v156, v[212:215], s[38:39] offset:576
	s_add_u32 s36, s0, 0x90000
	s_addc_u32 s37, s1, 0
	global_load_dwordx4 v[196:199], v156, s[36:37]
	global_load_dwordx4 v[204:207], v156, s[36:37] offset:64
	global_load_dwordx4 v[208:211], v156, s[36:37] offset:512
	global_load_dwordx4 v[212:215], v156, s[36:37] offset:576
	s_waitcnt vmcnt(16)
;     __device__ __forceinline__ void operator()(const f32x4 (&acc)[2][2][4][2], const pg8::Unit& u, int wr, int wc, int fr, int fq) const {
;     ...
;         for (int ai = 0; ai < 2; ++ai)
; #pragma unroll
;             for (int m = 0; m < 4; ++m) {
;                 const size_t off = (size_t)(row0 + ai * 128 + m * 16) * DM + col0;
; #pragma unroll
;                 for (int bj = 0; bj < 2; ++bj)
; #pragma unroll
;                     for (int n = 0; n < 2; ++n) {
;                         const f32x4 xv = *(const f32x4*)(xin + off + bj * 128 + n * 16);
;                         *(f32x4*)(out + off + bj * 128 + n * 16) = xv + gv[bj][n] * acc[ai][bj][m][n];
;                     }
;                 if (m == 3) asm volatile("" ::: "memory");
;             }
	v_pk_fma_f32 v[166:167], v[82:83], v[142:143], v[166:167]
	v_pk_fma_f32 v[164:165], v[80:81], v[140:141], v[164:165]
	v_pk_fma_f32 v[170:171], v[78:79], v[138:139], v[170:171]
	v_pk_fma_f32 v[168:169], v[76:77], v[136:137], v[168:169]
	v_pk_fma_f32 v[174:175], v[70:71], v[134:135], v[174:175]
	v_pk_fma_f32 v[172:173], v[68:69], v[132:133], v[172:173]
	v_pk_fma_f32 v[178:179], v[66:67], v[130:131], v[178:179]
	v_pk_fma_f32 v[176:177], v[64:65], v[128:129], v[176:177]
	s_add_u32 s38, s8, 0x30000
	s_addc_u32 s39, s9, 0
	global_store_dwordx4 v156, v[164:167], s[38:39]
	global_store_dwordx4 v156, v[168:171], s[38:39] offset:64
	global_store_dwordx4 v156, v[172:175], s[38:39] offset:512
	global_store_dwordx4 v156, v[176:179], s[38:39] offset:576
	s_add_u32 s36, s0, 0xa0000
	s_addc_u32 s37, s1, 0
	global_load_dwordx4 v[164:167], v156, s[36:37]
	global_load_dwordx4 v[168:171], v156, s[36:37] offset:64
	global_load_dwordx4 v[172:175], v156, s[36:37] offset:512
	global_load_dwordx4 v[176:179], v156, s[36:37] offset:576
	s_waitcnt vmcnt(16)
	v_pk_fma_f32 v[182:183], v[62:63], v[142:143], v[182:183]
	v_pk_fma_f32 v[180:181], v[60:61], v[140:141], v[180:181]
	v_pk_fma_f32 v[186:187], v[58:59], v[138:139], v[186:187]
	v_pk_fma_f32 v[184:185], v[56:57], v[136:137], v[184:185]
	v_pk_fma_f32 v[190:191], v[54:55], v[134:135], v[190:191]
	v_pk_fma_f32 v[188:189], v[52:53], v[132:133], v[188:189]
	v_pk_fma_f32 v[194:195], v[42:43], v[130:131], v[194:195]
	v_pk_fma_f32 v[192:193], v[40:41], v[128:129], v[192:193]
	s_add_u32 s38, s8, 0x80000
	s_addc_u32 s39, s9, 0
	global_store_dwordx4 v156, v[180:183], s[38:39]
	global_store_dwordx4 v156, v[184:187], s[38:39] offset:64
	global_store_dwordx4 v156, v[188:191], s[38:39] offset:512
	global_store_dwordx4 v156, v[192:195], s[38:39] offset:576
	s_add_u32 s36, s0, 0xb0000
	s_addc_u32 s37, s1, 0
	global_load_dwordx4 v[180:183], v156, s[36:37]
	global_load_dwordx4 v[184:187], v156, s[36:37] offset:64
	global_load_dwordx4 v[188:191], v156, s[36:37] offset:512
	global_load_dwordx4 v[192:195], v156, s[36:37] offset:576
	s_waitcnt vmcnt(16)
	v_pk_fma_f32 v[198:199], v[50:51], v[142:143], v[198:199]
	v_pk_fma_f32 v[196:197], v[48:49], v[140:141], v[196:197]
	v_pk_fma_f32 v[206:207], v[46:47], v[138:139], v[206:207]
	v_pk_fma_f32 v[204:205], v[44:45], v[136:137], v[204:205]
	v_pk_fma_f32 v[210:211], v[38:39], v[134:135], v[210:211]
	v_pk_fma_f32 v[208:209], v[36:37], v[132:133], v[208:209]
	v_pk_fma_f32 v[214:215], v[26:27], v[130:131], v[214:215]
	v_pk_fma_f32 v[212:213], v[24:25], v[128:129], v[212:213]
	s_add_u32 s38, s8, 0x90000
	s_addc_u32 s39, s9, 0
	global_store_dwordx4 v156, v[196:199], s[38:39]
	global_store_dwordx4 v156, v[204:207], s[38:39] offset:64
	global_store_dwordx4 v156, v[208:211], s[38:39] offset:512
	global_store_dwordx4 v156, v[212:215], s[38:39] offset:576
	s_waitcnt vmcnt(12)
	v_pk_fma_f32 v[166:167], v[34:35], v[142:143], v[166:167]
	v_pk_fma_f32 v[164:165], v[32:33], v[140:141], v[164:165]
	v_pk_fma_f32 v[170:171], v[30:31], v[138:139], v[170:171]
	v_pk_fma_f32 v[168:169], v[28:29], v[136:137], v[168:169]
	v_pk_fma_f32 v[174:175], v[22:23], v[134:135], v[174:175]
	v_pk_fma_f32 v[172:173], v[20:21], v[132:133], v[172:173]
	v_pk_fma_f32 v[178:179], v[10:11], v[130:131], v[178:179]
	v_pk_fma_f32 v[176:177], v[8:9], v[128:129], v[176:177]
	s_add_u32 s38, s8, 0xa0000
	s_addc_u32 s39, s9, 0
	global_store_dwordx4 v156, v[164:167], s[38:39]
	global_store_dwordx4 v156, v[168:171], s[38:39] offset:64
	global_store_dwordx4 v156, v[172:175], s[38:39] offset:512
	global_store_dwordx4 v156, v[176:179], s[38:39] offset:576
	s_waitcnt vmcnt(8)
	v_pk_fma_f32 v[182:183], v[18:19], v[142:143], v[182:183]
	v_pk_fma_f32 v[180:181], v[16:17], v[140:141], v[180:181]
	v_pk_fma_f32 v[186:187], v[14:15], v[138:139], v[186:187]
	v_pk_fma_f32 v[184:185], v[12:13], v[136:137], v[184:185]
	v_pk_fma_f32 v[190:191], v[6:7], v[134:135], v[190:191]
	v_pk_fma_f32 v[188:189], v[4:5], v[132:133], v[188:189]
	v_pk_fma_f32 v[194:195], v[2:3], v[130:131], v[194:195]
	v_pk_fma_f32 v[192:193], v[0:1], v[128:129], v[192:193]
	s_add_u32 s38, s8, 0xb0000
	s_addc_u32 s39, s9, 0
	global_store_dwordx4 v156, v[180:183], s[38:39]
	global_store_dwordx4 v156, v[184:187], s[38:39] offset:64
	global_store_dwordx4 v156, v[188:191], s[38:39] offset:512
	global_store_dwordx4 v156, v[192:195], s[38:39] offset:576
	s_cbranch_vccnz .LBB0_571
	s_andn2_b64 vcc, exec, s[6:7]
	s_cbranch_vccnz .LBB0_570
	s_barrier
	s_branch .LBB0_570

; __device__ __forceinline__ void fast_grid_barrier(unsigned* base, int seam, int tid) {
;     asm volatile("s_waitcnt vmcnt(0)" ::: "memory");
;     __syncthreads();
;     if (tid == 0) {
;         unsigned* cnt = base + seam * 128;
;         unsigned* flg = cnt + 64;
;         __builtin_amdgcn_fence(__ATOMIC_RELEASE, "agent");
;         asm volatile("s_waitcnt vmcnt(0)" ::: "memory");
;         const unsigned old = __hip_atomic_fetch_add(cnt, 1u, __ATOMIC_RELAXED, __HIP_MEMORY_SCOPE_AGENT);
;         if (old == gridDim.x - 1) __hip_atomic_store(flg, 1u, __ATOMIC_RELAXED, __HIP_MEMORY_SCOPE_AGENT);
;         else { unsigned sp = 0; while (__hip_atomic_load(flg, __ATOMIC_RELAXED, __HIP_MEMORY_SCOPE_AGENT) == 0u) { __builtin_amdgcn_s_sleep(2); if (++sp > (1u << 22)) break; } }
;         __builtin_amdgcn_fence(__ATOMIC_ACQUIRE, "agent");
;         asm volatile("s_waitcnt vmcnt(0)" ::: "memory");
;     }
;     __syncthreads();
; }
.LBB0_586:
	s_waitcnt lgkmcnt(0)
	s_cmp_lt_i32 s47, 6
	s_cbranch_scc1 .LBB0_603
	s_waitcnt vmcnt(0)
	v_cmp_eq_u32_e32 vcc, 0, v202
	s_barrier
	s_and_saveexec_b64 s[0:1], vcc
	s_cbranch_execz .LBB0_602
	s_load_dwordx2 s[4:5], s[84:85], 0x90
	s_lshl_b32 s3, s98, 6
	v_mov_b32_e32 v0, s3
	v_mov_b32_e32 v2, 1
	s_waitcnt lgkmcnt(0)
	s_add_u32 s4, s4, 0x1400
	s_addc_u32 s5, s5, 0
	global_atomic_add v1, v0, v2, s[4:5] offset:128 sc0
	s_mul_i32 s6, s99, 4
	s_add_i32 s6, s6, -1
	s_waitcnt vmcnt(0)
	v_cmp_ne_u32_e32 vcc, s6, v1
	s_cbranch_vccnz .Lsm4_follow
	buffer_wbl2 sc1
	s_waitcnt vmcnt(0)
	s_sub_u32 s6, s4, s3
	s_subb_u32 s7, s5, 0
	global_atomic_add v1, v0, v2, s[6:7] offset:2176 sc0
	s_mul_i32 s3, s100, 4
	s_add_i32 s3, s3, -1
	s_waitcnt vmcnt(0)
	v_cmp_ne_u32_e32 vcc, s3, v1
	v_mov_b32_e32 v1, 4
	s_cbranch_vccnz .Lsm4_wtop
	global_store_dword v0, v1, s[6:7] offset:2304 sc1
	s_branch .Lsm4_topdone

; __device__ __forceinline__ void fast_grid_barrier(unsigned* base, int seam, int tid) {
;     ...
;         asm volatile("s_waitcnt vmcnt(0)" ::: "memory");
;         const unsigned old = __hip_atomic_fetch_add(cnt, 1u, __ATOMIC_RELAXED, __HIP_MEMORY_SCOPE_AGENT);
;         if (old == gridDim.x - 1) __hip_atomic_store(flg, 1u, __ATOMIC_RELAXED, __HIP_MEMORY_SCOPE_AGENT);
;         else { unsigned sp = 0; while (__hip_atomic_load(flg, __ATOMIC_RELAXED, __HIP_MEMORY_SCOPE_AGENT) == 0u) { __builtin_amdgcn_s_sleep(2); if (++sp > (1u << 22)) break; } }
;         __builtin_amdgcn_fence(__ATOMIC_ACQUIRE, "agent");
;         asm volatile("s_waitcnt vmcnt(0)" ::: "memory");
.Lsm4_wtop_loop:
	global_load_dword v1, v0, s[6:7] offset:2304 sc1
	s_waitcnt vmcnt(0)
	v_cmp_le_u32_e32 vcc, 4, v1
	s_cbranch_vccnz .Lsm4_topdone
	s_sleep 1
	s_add_i32 s3, s3, -1
	s_cmp_lg_u32 s3, 0
	s_cbranch_scc1 .Lsm4_wtop_loop
.Lsm4_topdone:
	s_waitcnt vmcnt(0)
	buffer_inv sc1
	v_mov_b32_e32 v1, 4
	global_store_dword v0, v1, s[4:5] offset:1152 sc1
	s_waitcnt vmcnt(0)
	s_branch .Lsm4_done

; __device__ __forceinline__ void fast_grid_barrier(unsigned* base, int seam, int tid) {
;     ...
;         else { unsigned sp = 0; while (__hip_atomic_load(flg, __ATOMIC_RELAXED, __HIP_MEMORY_SCOPE_AGENT) == 0u) { __builtin_amdgcn_s_sleep(2); if (++sp > (1u << 22)) break; } }
;         __builtin_amdgcn_fence(__ATOMIC_ACQUIRE, "agent");
;         asm volatile("s_waitcnt vmcnt(0)" ::: "memory");
.Lsm4_follow_loop:
	global_load_dword v1, v0, s[4:5] offset:1152 sc1
	s_waitcnt vmcnt(0)
	v_cmp_le_u32_e32 vcc, 4, v1
	s_cbranch_vccnz .Lsm4_fdone
	s_sleep 1
	s_add_i32 s3, s3, -1
	s_cmp_lg_u32 s3, 0
	s_cbranch_scc1 .Lsm4_follow_loop

; __device__ __forceinline__ void fast_grid_barrier(unsigned* base, int seam, int tid) {
;     asm volatile("s_waitcnt vmcnt(0)" ::: "memory");
;     __syncthreads();
;     if (tid == 0) {
;         unsigned* cnt = base + seam * 128;
;         unsigned* flg = cnt + 64;
;         __builtin_amdgcn_fence(__ATOMIC_RELEASE, "agent");
;         asm volatile("s_waitcnt vmcnt(0)" ::: "memory");
;         const unsigned old = __hip_atomic_fetch_add(cnt, 1u, __ATOMIC_RELAXED, __HIP_MEMORY_SCOPE_AGENT);
;         if (old == gridDim.x - 1) __hip_atomic_store(flg, 1u, __ATOMIC_RELAXED, __HIP_MEMORY_SCOPE_AGENT);
;         else { unsigned sp = 0; while (__hip_atomic_load(flg, __ATOMIC_RELAXED, __HIP_MEMORY_SCOPE_AGENT) == 0u) { __builtin_amdgcn_s_sleep(2); if (++sp > (1u << 22)) break; } }
;         __builtin_amdgcn_fence(__ATOMIC_ACQUIRE, "agent");
;         asm volatile("s_waitcnt vmcnt(0)" ::: "memory");
;     }
;     __syncthreads();
; }
.LBB0_609:
	s_cmp_lt_i32 s47, 7
	s_cbranch_scc1 .LBB0_626
	s_waitcnt vmcnt(0)
	v_cmp_eq_u32_e32 vcc, 0, v202
	s_waitcnt vmcnt(0) lgkmcnt(0)
	s_barrier
	s_and_saveexec_b64 s[0:1], vcc
	s_cbranch_execz .LBB0_625
	s_load_dwordx2 s[4:5], s[84:85], 0x90
	s_lshl_b32 s3, s98, 6
	v_mov_b32_e32 v0, s3
	v_mov_b32_e32 v2, 1
	s_waitcnt lgkmcnt(0)
	s_add_u32 s4, s4, 0x1400
	s_addc_u32 s5, s5, 0
	global_atomic_add v1, v0, v2, s[4:5] offset:128 sc0
	s_mul_i32 s6, s99, 5
	s_add_i32 s6, s6, -1
	s_waitcnt vmcnt(0)
	v_cmp_ne_u32_e32 vcc, s6, v1
	s_cbranch_vccnz .Lsm5_follow
	buffer_wbl2 sc1
	s_waitcnt vmcnt(0)
	s_sub_u32 s6, s4, s3
	s_subb_u32 s7, s5, 0
	global_atomic_add v1, v0, v2, s[6:7] offset:2176 sc0
	s_mul_i32 s3, s100, 5
	s_add_i32 s3, s3, -1
	s_waitcnt vmcnt(0)
	v_cmp_ne_u32_e32 vcc, s3, v1
	v_mov_b32_e32 v1, 5
	s_cbranch_vccnz .Lsm5_wtop
	global_store_dword v0, v1, s[6:7] offset:2304 sc1
	s_branch .Lsm5_topdone

; __device__ __forceinline__ void fast_grid_barrier(unsigned* base, int seam, int tid) {
;     ...
;         asm volatile("s_waitcnt vmcnt(0)" ::: "memory");
;         const unsigned old = __hip_atomic_fetch_add(cnt, 1u, __ATOMIC_RELAXED, __HIP_MEMORY_SCOPE_AGENT);
;         if (old == gridDim.x - 1) __hip_atomic_store(flg, 1u, __ATOMIC_RELAXED, __HIP_MEMORY_SCOPE_AGENT);
;         else { unsigned sp = 0; while (__hip_atomic_load(flg, __ATOMIC_RELAXED, __HIP_MEMORY_SCOPE_AGENT) == 0u) { __builtin_amdgcn_s_sleep(2); if (++sp > (1u << 22)) break; } }
;         __builtin_amdgcn_fence(__ATOMIC_ACQUIRE, "agent");
;         asm volatile("s_waitcnt vmcnt(0)" ::: "memory");
.Lsm5_wtop_loop:
	global_load_dword v1, v0, s[6:7] offset:2304 sc1
	s_waitcnt vmcnt(0)
	v_cmp_le_u32_e32 vcc, 5, v1
	s_cbranch_vccnz .Lsm5_topdone
	s_sleep 1
	s_add_i32 s3, s3, -1
	s_cmp_lg_u32 s3, 0
	s_cbranch_scc1 .Lsm5_wtop_loop
.Lsm5_topdone:
	s_waitcnt vmcnt(0)
	buffer_inv sc1
	v_mov_b32_e32 v1, 5
	global_store_dword v0, v1, s[4:5] offset:1152 sc1
	s_waitcnt vmcnt(0)
	s_branch .Lsm5_done

; __device__ __forceinline__ void fast_grid_barrier(unsigned* base, int seam, int tid) {
;     ...
;         else { unsigned sp = 0; while (__hip_atomic_load(flg, __ATOMIC_RELAXED, __HIP_MEMORY_SCOPE_AGENT) == 0u) { __builtin_amdgcn_s_sleep(2); if (++sp > (1u << 22)) break; } }
;         __builtin_amdgcn_fence(__ATOMIC_ACQUIRE, "agent");
;         asm volatile("s_waitcnt vmcnt(0)" ::: "memory");
.Lsm5_follow_loop:
	global_load_dword v1, v0, s[4:5] offset:1152 sc1
	s_waitcnt vmcnt(0)
	v_cmp_le_u32_e32 vcc, 5, v1
	s_cbranch_vccnz .Lsm5_fdone
	s_sleep 1
	s_add_i32 s3, s3, -1
	s_cmp_lg_u32 s3, 0
	s_cbranch_scc1 .Lsm5_follow_loop

; __device__ __forceinline__ void fast_grid_barrier(unsigned* base, int seam, int tid) {
;     asm volatile("s_waitcnt vmcnt(0)" ::: "memory");
;     __syncthreads();
;     if (tid == 0) {
;         unsigned* cnt = base + seam * 128;
;         unsigned* flg = cnt + 64;
;         __builtin_amdgcn_fence(__ATOMIC_RELEASE, "agent");
;         asm volatile("s_waitcnt vmcnt(0)" ::: "memory");
;         const unsigned old = __hip_atomic_fetch_add(cnt, 1u, __ATOMIC_RELAXED, __HIP_MEMORY_SCOPE_AGENT);
;         if (old == gridDim.x - 1) __hip_atomic_store(flg, 1u, __ATOMIC_RELAXED, __HIP_MEMORY_SCOPE_AGENT);
;         else { unsigned sp = 0; while (__hip_atomic_load(flg, __ATOMIC_RELAXED, __HIP_MEMORY_SCOPE_AGENT) == 0u) { __builtin_amdgcn_s_sleep(2); if (++sp > (1u << 22)) break; } }
;         __builtin_amdgcn_fence(__ATOMIC_ACQUIRE, "agent");
;         asm volatile("s_waitcnt vmcnt(0)" ::: "memory");
;     }
;     __syncthreads();
; }
.LBB0_692:
	s_waitcnt vmcnt(0)
	v_cmp_eq_u32_e32 vcc, 0, v202
	s_waitcnt vmcnt(0) lgkmcnt(0)
	s_barrier
	s_and_saveexec_b64 s[0:1], vcc
	s_cbranch_execz .LBB0_707
	s_load_dwordx2 s[4:5], s[84:85], 0x90
	s_lshl_b32 s3, s98, 6
	v_mov_b32_e32 v0, s3
	v_mov_b32_e32 v2, 1
	s_waitcnt lgkmcnt(0)
	s_add_u32 s4, s4, 0x1400
	s_addc_u32 s5, s5, 0
	global_atomic_add v1, v0, v2, s[4:5] offset:128 sc0
	s_mul_i32 s6, s99, 6
	s_add_i32 s6, s6, -1
	s_waitcnt vmcnt(0)
	v_cmp_ne_u32_e32 vcc, s6, v1
	s_cbranch_vccnz .Lsm6_follow
	buffer_wbl2 sc1
	s_waitcnt vmcnt(0)
	s_sub_u32 s6, s4, s3
	s_subb_u32 s7, s5, 0
	global_atomic_add v1, v0, v2, s[6:7] offset:2176 sc0
	s_mul_i32 s3, s100, 6
	s_add_i32 s3, s3, -1
	s_waitcnt vmcnt(0)
	v_cmp_ne_u32_e32 vcc, s3, v1
	v_mov_b32_e32 v1, 6
	s_cbranch_vccnz .Lsm6_wtop
	global_store_dword v0, v1, s[6:7] offset:2304 sc1
	s_branch .Lsm6_topdone

; __device__ __forceinline__ void fast_grid_barrier(unsigned* base, int seam, int tid) {
;     ...
;         asm volatile("s_waitcnt vmcnt(0)" ::: "memory");
;         const unsigned old = __hip_atomic_fetch_add(cnt, 1u, __ATOMIC_RELAXED, __HIP_MEMORY_SCOPE_AGENT);
;         if (old == gridDim.x - 1) __hip_atomic_store(flg, 1u, __ATOMIC_RELAXED, __HIP_MEMORY_SCOPE_AGENT);
;         else { unsigned sp = 0; while (__hip_atomic_load(flg, __ATOMIC_RELAXED, __HIP_MEMORY_SCOPE_AGENT) == 0u) { __builtin_amdgcn_s_sleep(2); if (++sp > (1u << 22)) break; } }
;         __builtin_amdgcn_fence(__ATOMIC_ACQUIRE, "agent");
;         asm volatile("s_waitcnt vmcnt(0)" ::: "memory");
.Lsm6_wtop_loop:
	global_load_dword v1, v0, s[6:7] offset:2304 sc1
	s_waitcnt vmcnt(0)
	v_cmp_le_u32_e32 vcc, 6, v1
	s_cbranch_vccnz .Lsm6_topdone
	s_sleep 1
	s_add_i32 s3, s3, -1
	s_cmp_lg_u32 s3, 0
	s_cbranch_scc1 .Lsm6_wtop_loop
.Lsm6_topdone:
	s_waitcnt vmcnt(0)
	buffer_inv sc1
	v_mov_b32_e32 v1, 6
	global_store_dword v0, v1, s[4:5] offset:1152 sc1
	s_waitcnt vmcnt(0)
	s_branch .Lsm6_done

; __device__ __forceinline__ void fast_grid_barrier(unsigned* base, int seam, int tid) {
;     ...
;         else { unsigned sp = 0; while (__hip_atomic_load(flg, __ATOMIC_RELAXED, __HIP_MEMORY_SCOPE_AGENT) == 0u) { __builtin_amdgcn_s_sleep(2); if (++sp > (1u << 22)) break; } }
;         __builtin_amdgcn_fence(__ATOMIC_ACQUIRE, "agent");
;         asm volatile("s_waitcnt vmcnt(0)" ::: "memory");
.Lsm6_follow_loop:
	global_load_dword v1, v0, s[4:5] offset:1152 sc1
	s_waitcnt vmcnt(0)
	v_cmp_le_u32_e32 vcc, 6, v1
	s_cbranch_vccnz .Lsm6_fdone
	s_sleep 1
	s_add_i32 s3, s3, -1
	s_cmp_lg_u32 s3, 0
	s_cbranch_scc1 .Lsm6_follow_loop

; #define LAS __attribute__((address_space(3)))
; #define p3_fetch(a_, b_, c_) (ubase + p3_fetch_(a_, b_, c_, pre, pre2, nxt_))
;     volatile LAS int* s_unit = (volatile LAS int*)(lds + LDS_BYTES - 64);
;     ...
;     int pre = 0, pre2 = 0, nxt_ = 0; if (tid == 0) { pre = (int)atomicAdd(counter, 1u); pre2 = (int)atomicAdd(counter, 1u); }
;     int u = p3_fetch(s_unit, counter, tid);
; template <int PH>
; __device__ __forceinline__ void run_phase(LAS unsigned char* lds, int tid, int wid, int lane) {
;     ...
;         } else if constexpr (sub == 2) {
;             LayerP lp;
;             lp.gv = a.in[6] + l * 256; lp.gws = a.in[7] + (size_t)l * 4 * 128 * 128; lp.gbs = a.in[8] + l * 512; lp.convw = a.in[9] + l * 4 * 768; lp.convb = a.in[10] + l * 768;
;             lp.bi = a.in[11] + l * 4; lp.bfv = a.in[12] + l * 4; lp.hn = a.in[13] + l * 384; lp.gq = a.in[14] + l * 64; lp.gk = a.in[15] + l * 64; lp.halo = (const bf16*)(ws + WS_HALO);
;             p3_phase(lds, PJ, gate, H, lp, (unsigned*)(ws + WS_CTL) + 64 * l, tid, P3_WID, lane);
.LBB0_708:
	s_cmp_gt_i32 s46, 7
	s_cselect_b64 s[0:1], -1, 0
	s_cmp_lt_i32 s47, 8
	s_cselect_b64 s[4:5], -1, 0
	s_or_b64 s[0:1], s[0:1], s[4:5]
	s_and_b64 vcc, exec, s[0:1]
	s_cbranch_vccnz .LBB0_1086
	s_mov_b64 s[0:1], s[84:85]
	s_load_dwordx16 s[4:19], s[0:1], 0x30
	s_waitcnt vmcnt(0)
	v_mov_b32_e32 v0, 0
	v_mov_b32_e32 v135, 0
	s_load_dwordx2 s[82:83], s[0:1], 0x90
	s_waitcnt lgkmcnt(0)
	v_writelane_b32 v248, s4, 7
	s_nop 1
	v_writelane_b32 v248, s5, 8
	v_writelane_b32 v248, s6, 9
	v_writelane_b32 v248, s7, 10
	v_writelane_b32 v248, s8, 11
	v_writelane_b32 v248, s9, 12
	v_writelane_b32 v248, s10, 13
	v_writelane_b32 v248, s11, 14
	v_writelane_b32 v248, s12, 15
	v_writelane_b32 v248, s13, 16
	v_writelane_b32 v248, s14, 17
	v_writelane_b32 v248, s15, 18
	v_writelane_b32 v248, s16, 19
	v_writelane_b32 v248, s17, 20
	v_writelane_b32 v248, s18, 21
	v_writelane_b32 v248, s19, 22
	s_load_dwordx4 s[4:7], s[0:1], 0x70
	s_waitcnt lgkmcnt(0)
	v_writelane_b32 v248, s4, 31
	s_nop 1
	v_writelane_b32 v248, s5, 32
	v_writelane_b32 v248, s6, 33
	v_writelane_b32 v248, s7, 34
	v_cmp_eq_u32_e64 s[4:5], 0, v202
	s_mov_b64 s[0:1], exec
	s_nop 0
	v_writelane_b32 v249, s4, 8
	s_nop 1
	v_writelane_b32 v249, s5, 9
	s_and_b64 s[4:5], s[0:1], s[4:5]
	s_mov_b64 exec, s[4:5]
	s_cbranch_execz .LBB0_715
	s_mov_b64 s[6:7], exec
	v_mbcnt_lo_u32_b32 v0, s6, 0
	v_mbcnt_hi_u32_b32 v0, s7, v0
	v_cmp_eq_u32_e32 vcc, 0, v0
	s_and_saveexec_b64 s[4:5], vcc
	s_cbranch_execz .LBB0_712
	s_bcnt1_i32_b64 s3, s[6:7]
	v_mov_b32_e32 v1, 0
	v_mov_b32_e32 v2, s3
	s_nop 0

; #define LAS __attribute__((address_space(3)))
; #define LBAR() do { asm volatile("s_waitcnt lgkmcnt(0)" ::: "memory"); __builtin_amdgcn_s_barrier(); asm volatile("" ::: "memory"); } while (0)
; __device__ __forceinline__ int p3_fetch_(volatile LAS int* s_unit, unsigned* counter, int tid, int& pre, int& pre2, int& nxt) {
;     LBAR();
;     if (tid == 0) { s_unit[0] = pre; s_unit[1] = pre2; }
;     LBAR();
;     const int u = __builtin_amdgcn_readfirstlane(s_unit[0]);
;     nxt = __builtin_amdgcn_readfirstlane(s_unit[1]);
;     if (tid == 0) { pre = pre2; pre2 = (int)atomicAdd(counter, 1u); }
;     return u;
.LBB0_720:
	s_or_b64 exec, exec, s[4:5]
	s_waitcnt vmcnt(0)
	v_readfirstlane_b32 s3, v2
	v_mov_b32_e32 v135, v0
	s_nop 0
	v_add_u32_e32 v147, s3, v1
	v_add_u32_e32 v147, 0x100, v147

; #define LAS __attribute__((address_space(3)))
; #define LBAR() do { asm volatile("s_waitcnt lgkmcnt(0)" ::: "memory"); __builtin_amdgcn_s_barrier(); asm volatile("" ::: "memory"); } while (0)
; #define p3_fetch(a_, b_, c_) (ubase + p3_fetch_(a_, b_, c_, pre, pre2, nxt_))
; __device__ __forceinline__ int p3_fetch_(volatile LAS int* s_unit, unsigned* counter, int tid, int& pre, int& pre2, int& nxt) {
;     LBAR();
;     if (tid == 0) { s_unit[0] = pre; s_unit[1] = pre2; }
;     LBAR();
;     const int u = __builtin_amdgcn_readfirstlane(s_unit[0]);
;     nxt = __builtin_amdgcn_readfirstlane(s_unit[1]);
;     if (tid == 0) { pre = pre2; pre2 = (int)atomicAdd(counter, 1u); }
;     return u;
;     ...
;     while (u < N_ML && u < uend) { mlstm_unit(lds, P, lp.halo, gate, Y, lp.convw, lp.convb, lp.bi, lp.bfv, lp.hn, u >> 2, u & 3, tid, wid, lane, mode); u = p3_fetch(s_unit, counter, tid); }
.LBB0_838:
	s_or_b64 exec, exec, s[4:5]
	s_waitcnt vmcnt(0)
	v_readfirstlane_b32 s4, v2
	v_mov_b32_e32 v135, v147
	s_nop 0
	v_add_u32_e32 v122, s4, v0
	v_add_u32_e32 v122, 0x100, v122

; #define LAS __attribute__((address_space(3)))
; #define LBAR() do { asm volatile("s_waitcnt lgkmcnt(0)" ::: "memory"); __builtin_amdgcn_s_barrier(); asm volatile("" ::: "memory"); } while (0)
; #define p3_fetch(a_, b_, c_) (ubase + p3_fetch_(a_, b_, c_, pre, pre2, nxt_))
; __device__ __forceinline__ int p3_fetch_(volatile LAS int* s_unit, unsigned* counter, int tid, int& pre, int& pre2, int& nxt) {
;     LBAR();
;     if (tid == 0) { s_unit[0] = pre; s_unit[1] = pre2; }
;     LBAR();
;     const int u = __builtin_amdgcn_readfirstlane(s_unit[0]);
;     nxt = __builtin_amdgcn_readfirstlane(s_unit[1]);
;     if (tid == 0) { pre = pre2; pre2 = (int)atomicAdd(counter, 1u); }
;     return u;
;     ...
;         while (u < N_ML + N_AT && u < uend) {
;             const int idx = u - N_ML, qb = 15 - idx / 192, rem = idx % 192;
;             const int nu = ubase + nxt_; const bool nvalid = nu < N_ML + N_AT && nu < uend; const int nidx = nu - N_ML, nqb = 15 - nidx / 192, nrem = nidx % 192;
;             attn_unit(lds, P, Y, lp.gq, lp.gk, rem / 6, rem % 6, qb, tid, wid, lane, have, pf, nvalid, nrem / 6, nrem % 6, nqb);
;             have = nvalid;
;             u = p3_fetch(s_unit, counter, tid);
.LBB0_1006:
	s_or_b64 exec, exec, s[12:13]
	s_waitcnt vmcnt(0)
	v_readfirstlane_b32 s12, v25
	v_mov_b32_e32 v135, v122
	s_nop 0
	v_add_u32_e32 v41, s12, v24
	v_add_u32_e32 v41, 0x100, v41

; #define LAS __attribute__((address_space(3)))
; #define LBAR() do { asm volatile("s_waitcnt lgkmcnt(0)" ::: "memory"); __builtin_amdgcn_s_barrier(); asm volatile("" ::: "memory"); } while (0)
; #define p3_fetch(a_, b_, c_) (ubase + p3_fetch_(a_, b_, c_, pre, pre2, nxt_))
; __device__ __forceinline__ int p3_fetch_(volatile LAS int* s_unit, unsigned* counter, int tid, int& pre, int& pre2, int& nxt) {
;     LBAR();
;     if (tid == 0) { s_unit[0] = pre; s_unit[1] = pre2; }
;     LBAR();
;     const int u = __builtin_amdgcn_readfirstlane(s_unit[0]);
;     nxt = __builtin_amdgcn_readfirstlane(s_unit[1]);
;     if (tid == 0) { pre = pre2; pre2 = (int)atomicAdd(counter, 1u); }
;     return u;
;     ...
;     while (u < uend) { const int idx = u - N_ML - N_AT; gmlp_unit(lds, P, Y, lp.gws, lp.gbs, lp.gv, idx >> 4, (idx >> 2) & 3, idx & 3, tid, wid, lane); u = p3_fetch(s_unit, counter, tid); }
.LBB0_1052:
	s_or_b64 exec, exec, s[16:17]
	s_waitcnt vmcnt(0) lgkmcnt(0)
	v_readfirstlane_b32 s0, v1
	v_mov_b32_e32 v135, v41
	s_nop 0
	v_add_u32_e32 v0, s0, v0
	v_add_u32_e32 v0, 0x100, v0

; __device__ __forceinline__ void fast_grid_barrier(unsigned* base, int seam, int tid) {
;     asm volatile("s_waitcnt vmcnt(0)" ::: "memory");
;     __syncthreads();
;     if (tid == 0) {
;         unsigned* cnt = base + seam * 128;
;         unsigned* flg = cnt + 64;
;         __builtin_amdgcn_fence(__ATOMIC_RELEASE, "agent");
;         asm volatile("s_waitcnt vmcnt(0)" ::: "memory");
;         const unsigned old = __hip_atomic_fetch_add(cnt, 1u, __ATOMIC_RELAXED, __HIP_MEMORY_SCOPE_AGENT);
;         if (old == gridDim.x - 1) __hip_atomic_store(flg, 1u, __ATOMIC_RELAXED, __HIP_MEMORY_SCOPE_AGENT);
;         else { unsigned sp = 0; while (__hip_atomic_load(flg, __ATOMIC_RELAXED, __HIP_MEMORY_SCOPE_AGENT) == 0u) { __builtin_amdgcn_s_sleep(2); if (++sp > (1u << 22)) break; } }
;         __builtin_amdgcn_fence(__ATOMIC_ACQUIRE, "agent");
;         asm volatile("s_waitcnt vmcnt(0)" ::: "memory");
;     }
;     __syncthreads();
; }
.LBB0_1069:
	s_waitcnt lgkmcnt(0)
	s_cmp_lt_i32 s47, 9
	s_cbranch_scc1 .LBB0_1086
	s_waitcnt vmcnt(0)
	s_barrier
	s_mov_b64 s[0:1], exec
	v_readlane_b32 s4, v249, 8
	v_readlane_b32 s5, v249, 9
	s_and_b64 s[4:5], s[0:1], s[4:5]
	s_mov_b64 exec, s[4:5]
	s_cbranch_execz .LBB0_1085
	s_load_dwordx2 s[4:5], s[84:85], 0x90
	s_lshl_b32 s3, s98, 6
	v_mov_b32_e32 v0, s3
	v_mov_b32_e32 v2, 1
	s_waitcnt lgkmcnt(0)
	s_add_u32 s4, s4, 0x1400
	s_addc_u32 s5, s5, 0
	global_atomic_add v1, v0, v2, s[4:5] offset:128 sc0
	s_mul_i32 s6, s99, 7
	s_add_i32 s6, s6, -1
	s_waitcnt vmcnt(0)
	v_cmp_ne_u32_e32 vcc, s6, v1
	s_cbranch_vccnz .Lsm7_follow
	buffer_wbl2 sc1
	s_waitcnt vmcnt(0)
	s_sub_u32 s6, s4, s3
	s_subb_u32 s7, s5, 0
	global_atomic_add v1, v0, v2, s[6:7] offset:2176 sc0
	s_mul_i32 s3, s100, 7
	s_add_i32 s3, s3, -1
	s_waitcnt vmcnt(0)
	v_cmp_ne_u32_e32 vcc, s3, v1
	v_mov_b32_e32 v1, 7
	s_cbranch_vccnz .Lsm7_wtop
	global_store_dword v0, v1, s[6:7] offset:2304 sc1
	s_branch .Lsm7_topdone

; __device__ __forceinline__ void fast_grid_barrier(unsigned* base, int seam, int tid) {
;     ...
;         asm volatile("s_waitcnt vmcnt(0)" ::: "memory");
;         const unsigned old = __hip_atomic_fetch_add(cnt, 1u, __ATOMIC_RELAXED, __HIP_MEMORY_SCOPE_AGENT);
;         if (old == gridDim.x - 1) __hip_atomic_store(flg, 1u, __ATOMIC_RELAXED, __HIP_MEMORY_SCOPE_AGENT);
;         else { unsigned sp = 0; while (__hip_atomic_load(flg, __ATOMIC_RELAXED, __HIP_MEMORY_SCOPE_AGENT) == 0u) { __builtin_amdgcn_s_sleep(2); if (++sp > (1u << 22)) break; } }
;         __builtin_amdgcn_fence(__ATOMIC_ACQUIRE, "agent");
;         asm volatile("s_waitcnt vmcnt(0)" ::: "memory");
.Lsm7_wtop_loop:
	global_load_dword v1, v0, s[6:7] offset:2304 sc1
	s_waitcnt vmcnt(0)
	v_cmp_le_u32_e32 vcc, 7, v1
	s_cbranch_vccnz .Lsm7_topdone
	s_sleep 1
	s_add_i32 s3, s3, -1
	s_cmp_lg_u32 s3, 0
	s_cbranch_scc1 .Lsm7_wtop_loop
.Lsm7_topdone:
	s_waitcnt vmcnt(0)
	buffer_inv sc1
	v_mov_b32_e32 v1, 7
	global_store_dword v0, v1, s[4:5] offset:1152 sc1
	s_waitcnt vmcnt(0)
	s_branch .Lsm7_done

; __device__ __forceinline__ void fast_grid_barrier(unsigned* base, int seam, int tid) {
;     ...
;         else { unsigned sp = 0; while (__hip_atomic_load(flg, __ATOMIC_RELAXED, __HIP_MEMORY_SCOPE_AGENT) == 0u) { __builtin_amdgcn_s_sleep(2); if (++sp > (1u << 22)) break; } }
;         __builtin_amdgcn_fence(__ATOMIC_ACQUIRE, "agent");
;         asm volatile("s_waitcnt vmcnt(0)" ::: "memory");
.Lsm7_follow_loop:
	global_load_dword v1, v0, s[4:5] offset:1152 sc1
	s_waitcnt vmcnt(0)
	v_cmp_le_u32_e32 vcc, 7, v1
	s_cbranch_vccnz .Lsm7_fdone
	s_sleep 1
	s_add_i32 s3, s3, -1
	s_cmp_lg_u32 s3, 0
	s_cbranch_scc1 .Lsm7_follow_loop
